# loop-edge edit: up K-loop scalar bookkeeping (back-edge increments + next-iteration address selects) moved into the last MFMA block shadow, off the post-barrier path
# baseline (speedup 1.0000x reference)
; #define PG8_STAGE(bufoff, gbase, voff) do { _Pragma("unroll") for (int _i = 0; _i < 2; ++_i) \
;         __builtin_amdgcn_global_load_lds((const unsigned*)((const char*)(gbase) + (voff)[_i]), (PG8_LAS unsigned*)(lds + (bufoff) + ldsw + _i * 8192), 16, 0, 0); } while (0)
; #define PG8_LDA(dst, b, h) do { _Pragma("unroll") for (int m = 0; m < 4; ++m) _Pragma("unroll") for (int k = 0; k < 2; ++k) dst[m][k] = *(const PG8_LAS bf16x8*)(lds + PG8_SA(b, h) + aoff + m * 2048 + k * 1024); } while (0)
; #define PG8_LDB(dst, b, h) do { _Pragma("unroll") for (int n = 0; n < 2; ++n) _Pragma("unroll") for (int k = 0; k < 2; ++k) dst[n][k] = *(const PG8_LAS bf16x8*)(lds + PG8_SB(b, h) + boff + n * 2048 + k * 1024); } while (0)
; #define PG8_WAIT_V(n) asm volatile("s_waitcnt vmcnt(" #n ")" ::: "memory")
; #define PG8_WAIT_L(n) asm volatile("s_waitcnt lgkmcnt(" #n ")" ::: "memory")
; template <class Epi, class Sched, bool ALIGN_EPI = true>
; __device__ __forceinline__ void gemm_phase(PG8_LAS unsigned char* lds, const Gemm g, const Sched& S, const Epi& E, const int tid) {
;     ...
;         const bool has_next = S.next(ui + 1, nxt);
;         const char* nA = has_next ? (const char*)g.A + (size_t)nxt.pm * tstepA + (size_t)nxt.grp * g.gsA + (size_t)nxt.kt0 * kstep : cA;
;         const char* nB = has_next ? (const char*)g.Bt + (size_t)nxt.pn * tstepB + (size_t)nxt.grp * g.gsB + (size_t)nxt.kt0 * kstep : cB;
;         const int nt = cur.nkt;
;         for (int t = 0; t < nt; t += 2) {
;             const bool last = (t == nt - 2);
;             const char* a1 = cA + (size_t)(t + 1) * kstep;
;             const char* a2 = last ? nA : cA + (size_t)(t + 2) * kstep; const char* b2 = last ? nB : cB + (size_t)(t + 2) * kstep;
;             const char* a3 = a2 + kstep; const char* b3 = b2 + kstep;
;             if (last && has_next) S.a_ready(nxt);
;             PG8_LDB(B0, 0, 0); PG8_LDB(B1, 0, 1); PG8_SCHED; PG8_LDA(At, 0, 0); PG8_STAGE(PG8_SA(1, 1), a1 + hstepA, voffA);
;             PG8_WAIT_V(8); PG8_WAIT_L(0); PG8_BAR; PG8_MMA(0, 0, At, B0); PG8_MMA(0, 1, At, B1); PG8_BAR; PG8_SCHED;
;     ...
; #pragma unroll
;         for (int a = 0; a < 2; ++a)
; #pragma unroll
;             for (int b = 0; b < 2; ++b)
; #pragma unroll
;                 for (int m = 0; m < 4; ++m)
; #pragma unroll
;                     for (int n = 0; n < 2; ++n) acc[a][b][m][n] = (f32x4){0.f, 0.f, 0.f, 0.f};
.LBB0_1237:
	s_ashr_i32 s13, s12, 31
	s_lshl_b64 s[0:1], s[12:13], 20
	s_add_u32 s0, s81, s0
	s_addc_u32 s1, s82, s1
	s_and_b64 s[18:19], s[50:51], exec
	s_cselect_b32 s8, s1, s75
	s_cselect_b32 s11, s0, s74
	s_ashr_i32 s23, s22, 31
	s_lshl_b64 s[18:19], s[22:23], 20
	s_add_u32 s70, s83, s18
	s_addc_u32 s71, s84, s19
	s_and_b64 s[18:19], s[50:51], exec
	s_cselect_b32 s13, s71, s77
	s_cselect_b32 s18, s70, s76
	s_add_u32 s74, s74, 0x80080
	s_addc_u32 s75, s75, 0
	s_add_u32 s19, s76, 0x100
	v_mov_b32_e32 v12, 0
	s_addc_u32 s20, s77, 0
	s_mov_b32 s21, -2
	v_mov_b32_e32 v13, v12
	v_mov_b64_e32 v[14:15], v[12:13]
	v_mov_b64_e32 v[16:17], v[12:13]
	v_mov_b64_e32 v[18:19], v[12:13]
	v_mov_b64_e32 v[20:21], v[12:13]
	v_mov_b64_e32 v[22:23], v[12:13]
	v_mov_b64_e32 v[24:25], v[12:13]
	v_mov_b64_e32 v[26:27], v[12:13]
	v_mov_b64_e32 v[36:37], v[12:13]
	v_mov_b64_e32 v[38:39], v[12:13]
	v_mov_b64_e32 v[40:41], v[12:13]
	v_mov_b64_e32 v[42:43], v[12:13]
	v_mov_b64_e32 v[52:53], v[12:13]
	v_mov_b64_e32 v[54:55], v[12:13]
	s_waitcnt vmcnt(0)
	v_mov_b64_e32 v[56:57], v[12:13]
	v_mov_b64_e32 v[58:59], v[12:13]
	v_mov_b64_e32 v[4:5], v[12:13]
	v_mov_b64_e32 v[6:7], v[12:13]
	v_mov_b64_e32 v[8:9], v[12:13]
	v_mov_b64_e32 v[10:11], v[12:13]
	v_mov_b64_e32 v[28:29], v[12:13]
	v_mov_b64_e32 v[30:31], v[12:13]
	v_mov_b64_e32 v[32:33], v[12:13]
	v_mov_b64_e32 v[34:35], v[12:13]
	v_mov_b64_e32 v[44:45], v[12:13]
	v_mov_b64_e32 v[46:47], v[12:13]
	v_mov_b64_e32 v[48:49], v[12:13]
	v_mov_b64_e32 v[50:51], v[12:13]
	v_mov_b64_e32 v[60:61], v[12:13]
	v_mov_b64_e32 v[62:63], v[12:13]
	v_mov_b64_e32 v[64:65], v[12:13]
	v_mov_b64_e32 v[66:67], v[12:13]
	v_mov_b64_e32 v[108:109], v[12:13]
	v_mov_b64_e32 v[110:111], v[12:13]
	v_mov_b64_e32 v[112:113], v[12:13]
	v_mov_b64_e32 v[114:115], v[12:13]
	v_mov_b64_e32 v[116:117], v[12:13]
	v_mov_b64_e32 v[118:119], v[12:13]
	v_mov_b64_e32 v[120:121], v[12:13]
	v_mov_b64_e32 v[122:123], v[12:13]
	v_mov_b64_e32 v[132:133], v[12:13]
	v_mov_b64_e32 v[134:135], v[12:13]
	v_mov_b64_e32 v[136:137], v[12:13]
	v_mov_b64_e32 v[138:139], v[12:13]
	v_mov_b64_e32 v[148:149], v[12:13]
	v_mov_b64_e32 v[150:151], v[12:13]
	v_mov_b64_e32 v[152:153], v[12:13]
	v_mov_b64_e32 v[154:155], v[12:13]
	v_mov_b64_e32 v[68:69], v[12:13]
	v_mov_b64_e32 v[70:71], v[12:13]
	v_mov_b64_e32 v[80:81], v[12:13]
	v_mov_b64_e32 v[82:83], v[12:13]
	v_mov_b64_e32 v[124:125], v[12:13]
	v_mov_b64_e32 v[126:127], v[12:13]
	v_mov_b64_e32 v[128:129], v[12:13]
	v_mov_b64_e32 v[130:131], v[12:13]
	v_mov_b64_e32 v[140:141], v[12:13]
	v_mov_b64_e32 v[142:143], v[12:13]
	v_mov_b64_e32 v[144:145], v[12:13]
	v_mov_b64_e32 v[146:147], v[12:13]
	v_mov_b64_e32 v[156:157], v[12:13]
	v_mov_b64_e32 v[158:159], v[12:13]
	v_mov_b64_e32 v[160:161], v[12:13]
	v_mov_b64_e32 v[162:163], v[12:13]
	s_add_u32 s15, s74, 0xfff80080
	s_addc_u32 s16, s75, -1
	s_add_i32 s17, 0, 0x10000
	s_cmp_eq_u32 s21, 28
	s_cselect_b32 s79, s8, s16
	s_cselect_b32 s78, s11, s15
	s_cselect_b32 s77, s13, s20
	s_cselect_b32 s76, s18, s19
	s_add_i32 s15, 0, 0x14000
.LBB0_1238:
	v_add_u32_e32 v88, s17, v193
	v_add_u32_e32 v104, s15, v193
	ds_read_b128 v[72:75], v88
	ds_read_b128 v[76:79], v88 offset:1024
	ds_read_b128 v[84:87], v88 offset:2048
	ds_read_b128 v[88:91], v88 offset:3072
	ds_read_b128 v[92:95], v104
	ds_read_b128 v[96:99], v104 offset:1024
	ds_read_b128 v[100:103], v104 offset:2048
	ds_read_b128 v[104:107], v104 offset:3072
	s_add_i32 m0, s86, 0xc000
	ds_read_b128 v[164:167], v200
	ds_read_b128 v[168:171], v200 offset:1024
	ds_read_b128 v[172:175], v200 offset:2048
	ds_read_b128 v[176:179], v200 offset:3072
	ds_read_b128 v[202:205], v200 offset:4096
	ds_read_b128 v[210:213], v200 offset:5120
	ds_read_b128 v[214:217], v200 offset:6144
	ds_read_b128 v[218:221], v200 offset:7168
	global_load_lds_dwordx4 v186, s[74:75]
	s_add_i32 m0, s86, 0xe000
	s_nop 0
	global_load_lds_dwordx4 v188, s[74:75]
	s_waitcnt vmcnt(8)
	s_waitcnt lgkmcnt(0)
	s_barrier
	s_waitcnt lgkmcnt(0)
	v_mfma_f32_16x16x32_bf16 v[160:163], v[72:75], v[164:167], v[160:163]
	v_mfma_f32_16x16x32_bf16 v[160:163], v[76:79], v[168:171], v[160:163]
	v_mfma_f32_16x16x32_bf16 v[156:159], v[88:91], v[168:171], v[156:159]
	v_mfma_f32_16x16x32_bf16 v[156:159], v[84:87], v[164:167], v[156:159]
	v_mfma_f32_16x16x32_bf16 v[140:143], v[84:87], v[172:175], v[140:143]
	v_mfma_f32_16x16x32_bf16 v[140:143], v[88:91], v[176:179], v[140:143]
	v_mfma_f32_16x16x32_bf16 v[144:147], v[76:79], v[176:179], v[144:147]
	v_mfma_f32_16x16x32_bf16 v[144:147], v[72:75], v[172:175], v[144:147]
	v_mfma_f32_16x16x32_bf16 v[128:131], v[72:75], v[202:205], v[128:131]
	v_mfma_f32_16x16x32_bf16 v[128:131], v[76:79], v[210:213], v[128:131]
	v_mfma_f32_16x16x32_bf16 v[124:127], v[88:91], v[210:213], v[124:127]
	v_mfma_f32_16x16x32_bf16 v[124:127], v[84:87], v[202:205], v[124:127]
	v_mfma_f32_16x16x32_bf16 v[68:71], v[84:87], v[214:217], v[68:71]
	v_mfma_f32_16x16x32_bf16 v[68:71], v[88:91], v[218:221], v[68:71]
	v_mfma_f32_16x16x32_bf16 v[80:83], v[76:79], v[218:221], v[80:83]
	v_mfma_f32_16x16x32_bf16 v[80:83], v[72:75], v[214:217], v[80:83]
	v_mfma_f32_16x16x32_bf16 v[152:155], v[92:95], v[164:167], v[152:155]
	v_mfma_f32_16x16x32_bf16 v[152:155], v[96:99], v[168:171], v[152:155]
	v_mfma_f32_16x16x32_bf16 v[148:151], v[104:107], v[168:171], v[148:151]
	v_mfma_f32_16x16x32_bf16 v[148:151], v[100:103], v[164:167], v[148:151]
	v_mfma_f32_16x16x32_bf16 v[132:135], v[100:103], v[172:175], v[132:135]
	v_mfma_f32_16x16x32_bf16 v[132:135], v[104:107], v[176:179], v[132:135]
	v_mfma_f32_16x16x32_bf16 v[136:139], v[96:99], v[176:179], v[136:139]
	v_mfma_f32_16x16x32_bf16 v[136:139], v[92:95], v[172:175], v[136:139]
	v_mfma_f32_16x16x32_bf16 v[120:123], v[92:95], v[202:205], v[120:123]
	v_mfma_f32_16x16x32_bf16 v[120:123], v[96:99], v[210:213], v[120:123]
	v_mfma_f32_16x16x32_bf16 v[116:119], v[104:107], v[210:213], v[116:119]
	v_mfma_f32_16x16x32_bf16 v[116:119], v[100:103], v[202:205], v[116:119]
	v_mfma_f32_16x16x32_bf16 v[108:111], v[100:103], v[214:217], v[108:111]
	v_mfma_f32_16x16x32_bf16 v[108:111], v[104:107], v[218:221], v[108:111]
	v_mfma_f32_16x16x32_bf16 v[112:115], v[96:99], v[218:221], v[112:115]
	v_mfma_f32_16x16x32_bf16 v[112:115], v[92:95], v[214:217], v[112:115]
	s_barrier
; #define PG8_STAGE(bufoff, gbase, voff) do { _Pragma("unroll") for (int _i = 0; _i < 2; ++_i) \
;         __builtin_amdgcn_global_load_lds((const unsigned*)((const char*)(gbase) + (voff)[_i]), (PG8_LAS unsigned*)(lds + (bufoff) + ldsw + _i * 8192), 16, 0, 0); } while (0)
; #define PG8_LDA(dst, b, h) do { _Pragma("unroll") for (int m = 0; m < 4; ++m) _Pragma("unroll") for (int k = 0; k < 2; ++k) dst[m][k] = *(const PG8_LAS bf16x8*)(lds + PG8_SA(b, h) + aoff + m * 2048 + k * 1024); } while (0)
; #define PG8_LDB(dst, b, h) do { _Pragma("unroll") for (int n = 0; n < 2; ++n) _Pragma("unroll") for (int k = 0; k < 2; ++k) dst[n][k] = *(const PG8_LAS bf16x8*)(lds + PG8_SB(b, h) + boff + n * 2048 + k * 1024); } while (0)
; #define PG8_MMA(ai, bj, At, Bt) do { __builtin_amdgcn_s_setprio(1); _Pragma("unroll") for (int m = 0; m < 4; ++m) _Pragma("unroll") for (int n = 0; n < 2; ++n) _Pragma("unroll") for (int k = 0; k < 2; ++k) \
;         acc[ai][bj][m][n] = __builtin_amdgcn_mfma_f32_16x16x32_bf16(Bt[n][k], At[m][k], acc[ai][bj][m][n], 0, 0, 0); __builtin_amdgcn_s_setprio(0); } while (0)
; #define PG8_WAIT_V(n) asm volatile("s_waitcnt vmcnt(" #n ")" ::: "memory")
; #define PG8_WAIT_L(n) asm volatile("s_waitcnt lgkmcnt(" #n ")" ::: "memory")
; #define PG8_BAR __builtin_amdgcn_s_barrier()
; #define PG8_SCHED __builtin_amdgcn_sched_barrier(0)
; template <class Epi, class Sched, bool ALIGN_EPI = true>
; __device__ __forceinline__ void gemm_phase(PG8_LAS unsigned char* lds, const Gemm g, const Sched& S, const Epi& E, const int tid) {
;     ...
;             PG8_LDA(At, 0, 1); PG8_STAGE(PG8_SB(0, 0), b2, voffB); PG8_STAGE(PG8_SB(0, 1), b2 + hstepB, voffB); PG8_STAGE(PG8_SA(0, 0), a2, voffA);
;             PG8_WAIT_V(8); PG8_WAIT_L(0); PG8_BAR; PG8_MMA(1, 0, At, B0); PG8_MMA(1, 1, At, B1); PG8_BAR; PG8_SCHED;
;             PG8_LDB(B0, 1, 0); PG8_LDB(B1, 1, 1); PG8_SCHED; PG8_LDA(At, 1, 0); PG8_STAGE(PG8_SA(0, 1), a2 + hstepA, voffA);
;             PG8_WAIT_V(8); PG8_WAIT_L(0); PG8_BAR; PG8_MMA(0, 0, At, B0); PG8_MMA(0, 1, At, B1); PG8_BAR; PG8_SCHED;
;             PG8_LDA(At, 1, 1); PG8_STAGE(PG8_SB(1, 0), b3, voffB); PG8_STAGE(PG8_SB(1, 1), b3 + hstepB, voffB); PG8_STAGE(PG8_SA(1, 0), a3, voffA);
	s_add_i32 s16, s17, s85
	s_mov_b32 m0, s16
	ds_read_b128 v[164:167], v200 offset:16384
	ds_read_b128 v[168:171], v200 offset:17408
	ds_read_b128 v[172:175], v200 offset:18432
	ds_read_b128 v[176:179], v200 offset:19456
	ds_read_b128 v[202:205], v200 offset:20480
	ds_read_b128 v[210:213], v200 offset:21504
	ds_read_b128 v[214:217], v200 offset:22528
	ds_read_b128 v[218:221], v200 offset:23552
	global_load_lds_dwordx4 v2, s[76:77]
	s_add_i32 m0, s16, 0x2000
	s_add_u32 s96, s76, 0x80000
	s_addc_u32 s97, s77, 0
	s_add_i32 s15, s15, s85
	global_load_lds_dwordx4 v184, s[76:77]
	s_mov_b32 m0, s15
	s_nop 0
	global_load_lds_dwordx4 v2, s[96:97]
	s_add_i32 m0, s15, 0x2000
	s_nop 0
	global_load_lds_dwordx4 v184, s[96:97]
	s_mov_b32 m0, s86
	s_nop 0
	global_load_lds_dwordx4 v180, s[78:79]
	s_mov_b32 m0, s87
	s_nop 0
	global_load_lds_dwordx4 v182, s[78:79]
	s_waitcnt vmcnt(8)
	s_waitcnt lgkmcnt(0)
	s_barrier
	s_waitcnt lgkmcnt(0)
	v_mfma_f32_16x16x32_bf16 v[64:67], v[72:75], v[164:167], v[64:67]
	v_mfma_f32_16x16x32_bf16 v[64:67], v[76:79], v[168:171], v[64:67]
	v_mfma_f32_16x16x32_bf16 v[60:63], v[88:91], v[168:171], v[60:63]
	v_mfma_f32_16x16x32_bf16 v[60:63], v[84:87], v[164:167], v[60:63]
	v_mfma_f32_16x16x32_bf16 v[44:47], v[84:87], v[172:175], v[44:47]
	v_mfma_f32_16x16x32_bf16 v[44:47], v[88:91], v[176:179], v[44:47]
	v_mfma_f32_16x16x32_bf16 v[48:51], v[76:79], v[176:179], v[48:51]
	v_mfma_f32_16x16x32_bf16 v[48:51], v[72:75], v[172:175], v[48:51]
	v_mfma_f32_16x16x32_bf16 v[32:35], v[72:75], v[202:205], v[32:35]
	v_mfma_f32_16x16x32_bf16 v[32:35], v[76:79], v[210:213], v[32:35]
	v_mfma_f32_16x16x32_bf16 v[28:31], v[88:91], v[210:213], v[28:31]
	v_mfma_f32_16x16x32_bf16 v[28:31], v[84:87], v[202:205], v[28:31]
	v_mfma_f32_16x16x32_bf16 v[4:7], v[84:87], v[214:217], v[4:7]
	v_mfma_f32_16x16x32_bf16 v[4:7], v[88:91], v[218:221], v[4:7]
	v_mfma_f32_16x16x32_bf16 v[8:11], v[76:79], v[218:221], v[8:11]
	v_mfma_f32_16x16x32_bf16 v[8:11], v[72:75], v[214:217], v[8:11]
	v_mfma_f32_16x16x32_bf16 v[56:59], v[92:95], v[164:167], v[56:59]
	v_mfma_f32_16x16x32_bf16 v[56:59], v[96:99], v[168:171], v[56:59]
	v_mfma_f32_16x16x32_bf16 v[52:55], v[104:107], v[168:171], v[52:55]
	v_mfma_f32_16x16x32_bf16 v[52:55], v[100:103], v[164:167], v[52:55]
	v_mfma_f32_16x16x32_bf16 v[36:39], v[100:103], v[172:175], v[36:39]
	v_mfma_f32_16x16x32_bf16 v[36:39], v[104:107], v[176:179], v[36:39]
	v_mfma_f32_16x16x32_bf16 v[40:43], v[96:99], v[176:179], v[40:43]
	v_mfma_f32_16x16x32_bf16 v[40:43], v[92:95], v[172:175], v[40:43]
	v_mfma_f32_16x16x32_bf16 v[24:27], v[92:95], v[202:205], v[24:27]
	v_mfma_f32_16x16x32_bf16 v[24:27], v[96:99], v[210:213], v[24:27]
	v_mfma_f32_16x16x32_bf16 v[20:23], v[104:107], v[210:213], v[20:23]
	v_mfma_f32_16x16x32_bf16 v[20:23], v[100:103], v[202:205], v[20:23]
	v_mfma_f32_16x16x32_bf16 v[12:15], v[100:103], v[214:217], v[12:15]
	v_mfma_f32_16x16x32_bf16 v[12:15], v[104:107], v[218:221], v[12:15]
	v_mfma_f32_16x16x32_bf16 v[16:19], v[96:99], v[218:221], v[16:19]
	v_mfma_f32_16x16x32_bf16 v[16:19], v[92:95], v[214:217], v[16:19]
	s_barrier
	s_add_i32 s15, 0, 0x18000
	s_add_i32 s16, 0, 0x1c000
	v_add_u32_e32 v88, s15, v193
	v_add_u32_e32 v104, s16, v193
	ds_read_b128 v[72:75], v88
	ds_read_b128 v[76:79], v88 offset:1024
	ds_read_b128 v[84:87], v88 offset:2048
	ds_read_b128 v[88:91], v88 offset:3072
	ds_read_b128 v[92:95], v104
	ds_read_b128 v[96:99], v104 offset:1024
	ds_read_b128 v[100:103], v104 offset:2048
	ds_read_b128 v[104:107], v104 offset:3072
	s_add_u32 s78, s78, 0x80000
	s_addc_u32 s79, s79, 0
	s_mov_b32 m0, s88
	ds_read_b128 v[164:167], v200 offset:32768
	ds_read_b128 v[168:171], v200 offset:33792
	ds_read_b128 v[172:175], v200 offset:34816
	ds_read_b128 v[176:179], v200 offset:35840
	ds_read_b128 v[202:205], v200 offset:36864
	ds_read_b128 v[210:213], v200 offset:37888
	ds_read_b128 v[214:217], v200 offset:38912
	ds_read_b128 v[218:221], v200 offset:39936
	global_load_lds_dwordx4 v180, s[78:79]
	s_mov_b32 m0, s89
	s_nop 0
	global_load_lds_dwordx4 v182, s[78:79]
	s_waitcnt vmcnt(8)
	s_waitcnt lgkmcnt(0)
	s_barrier
; #define PG8_STAGE(bufoff, gbase, voff) do { _Pragma("unroll") for (int _i = 0; _i < 2; ++_i) \
;         __builtin_amdgcn_global_load_lds((const unsigned*)((const char*)(gbase) + (voff)[_i]), (PG8_LAS unsigned*)(lds + (bufoff) + ldsw + _i * 8192), 16, 0, 0); } while (0)
; #define PG8_LDA(dst, b, h) do { _Pragma("unroll") for (int m = 0; m < 4; ++m) _Pragma("unroll") for (int k = 0; k < 2; ++k) dst[m][k] = *(const PG8_LAS bf16x8*)(lds + PG8_SA(b, h) + aoff + m * 2048 + k * 1024); } while (0)
; #define PG8_LDB(dst, b, h) do { _Pragma("unroll") for (int n = 0; n < 2; ++n) _Pragma("unroll") for (int k = 0; k < 2; ++k) dst[n][k] = *(const PG8_LAS bf16x8*)(lds + PG8_SB(b, h) + boff + n * 2048 + k * 1024); } while (0)
; #define PG8_MMA(ai, bj, At, Bt) do { __builtin_amdgcn_s_setprio(1); _Pragma("unroll") for (int m = 0; m < 4; ++m) _Pragma("unroll") for (int n = 0; n < 2; ++n) _Pragma("unroll") for (int k = 0; k < 2; ++k) \
;         acc[ai][bj][m][n] = __builtin_amdgcn_mfma_f32_16x16x32_bf16(Bt[n][k], At[m][k], acc[ai][bj][m][n], 0, 0, 0); __builtin_amdgcn_s_setprio(0); } while (0)
; #define PG8_WAIT_V(n) asm volatile("s_waitcnt vmcnt(" #n ")" ::: "memory")
; #define PG8_WAIT_L(n) asm volatile("s_waitcnt lgkmcnt(" #n ")" ::: "memory")
; #define PG8_BAR __builtin_amdgcn_s_barrier()
; template <class Epi, class Sched, bool ALIGN_EPI = true>
; __device__ __forceinline__ void gemm_phase(PG8_LAS unsigned char* lds, const Gemm g, const Sched& S, const Epi& E, const int tid) {
;     ...
;         for (int t = 0; t < nt; t += 2) {
;             const bool last = (t == nt - 2);
;             const char* a1 = cA + (size_t)(t + 1) * kstep;
;             const char* a2 = last ? nA : cA + (size_t)(t + 2) * kstep; const char* b2 = last ? nB : cB + (size_t)(t + 2) * kstep;
;             const char* a3 = a2 + kstep; const char* b3 = b2 + kstep;
;     ...
;             PG8_LDB(B0, 1, 0); PG8_LDB(B1, 1, 1); PG8_SCHED; PG8_LDA(At, 1, 0); PG8_STAGE(PG8_SA(0, 1), a2 + hstepA, voffA);
;             PG8_WAIT_V(8); PG8_WAIT_L(0); PG8_BAR; PG8_MMA(0, 0, At, B0); PG8_MMA(0, 1, At, B1); PG8_BAR; PG8_SCHED;
;             PG8_LDA(At, 1, 1); PG8_STAGE(PG8_SB(1, 0), b3, voffB); PG8_STAGE(PG8_SB(1, 1), b3 + hstepB, voffB); PG8_STAGE(PG8_SA(1, 0), a3, voffA);
;             PG8_WAIT_V(8); PG8_WAIT_L(0); PG8_BAR; PG8_MMA(1, 0, At, B0); PG8_MMA(1, 1, At, B1); PG8_BAR; PG8_SCHED;
	s_waitcnt lgkmcnt(0)
	v_mfma_f32_16x16x32_bf16 v[160:163], v[72:75], v[164:167], v[160:163]
	v_mfma_f32_16x16x32_bf16 v[160:163], v[76:79], v[168:171], v[160:163]
	v_mfma_f32_16x16x32_bf16 v[156:159], v[88:91], v[168:171], v[156:159]
	v_mfma_f32_16x16x32_bf16 v[156:159], v[84:87], v[164:167], v[156:159]
	v_mfma_f32_16x16x32_bf16 v[140:143], v[84:87], v[172:175], v[140:143]
	v_mfma_f32_16x16x32_bf16 v[140:143], v[88:91], v[176:179], v[140:143]
	v_mfma_f32_16x16x32_bf16 v[144:147], v[76:79], v[176:179], v[144:147]
	v_mfma_f32_16x16x32_bf16 v[144:147], v[72:75], v[172:175], v[144:147]
	v_mfma_f32_16x16x32_bf16 v[128:131], v[72:75], v[202:205], v[128:131]
	v_mfma_f32_16x16x32_bf16 v[128:131], v[76:79], v[210:213], v[128:131]
	v_mfma_f32_16x16x32_bf16 v[124:127], v[88:91], v[210:213], v[124:127]
	v_mfma_f32_16x16x32_bf16 v[124:127], v[84:87], v[202:205], v[124:127]
	v_mfma_f32_16x16x32_bf16 v[68:71], v[84:87], v[214:217], v[68:71]
	v_mfma_f32_16x16x32_bf16 v[68:71], v[88:91], v[218:221], v[68:71]
	v_mfma_f32_16x16x32_bf16 v[80:83], v[76:79], v[218:221], v[80:83]
	v_mfma_f32_16x16x32_bf16 v[80:83], v[72:75], v[214:217], v[80:83]
	v_mfma_f32_16x16x32_bf16 v[152:155], v[92:95], v[164:167], v[152:155]
	v_mfma_f32_16x16x32_bf16 v[152:155], v[96:99], v[168:171], v[152:155]
	v_mfma_f32_16x16x32_bf16 v[148:151], v[104:107], v[168:171], v[148:151]
	v_mfma_f32_16x16x32_bf16 v[148:151], v[100:103], v[164:167], v[148:151]
	v_mfma_f32_16x16x32_bf16 v[132:135], v[100:103], v[172:175], v[132:135]
	v_mfma_f32_16x16x32_bf16 v[132:135], v[104:107], v[176:179], v[132:135]
	v_mfma_f32_16x16x32_bf16 v[136:139], v[96:99], v[176:179], v[136:139]
	v_mfma_f32_16x16x32_bf16 v[136:139], v[92:95], v[172:175], v[136:139]
	v_mfma_f32_16x16x32_bf16 v[120:123], v[92:95], v[202:205], v[120:123]
	v_mfma_f32_16x16x32_bf16 v[120:123], v[96:99], v[210:213], v[120:123]
	v_mfma_f32_16x16x32_bf16 v[116:119], v[104:107], v[210:213], v[116:119]
	v_mfma_f32_16x16x32_bf16 v[116:119], v[100:103], v[202:205], v[116:119]
	v_mfma_f32_16x16x32_bf16 v[108:111], v[100:103], v[214:217], v[108:111]
	v_mfma_f32_16x16x32_bf16 v[108:111], v[104:107], v[218:221], v[108:111]
	v_mfma_f32_16x16x32_bf16 v[112:115], v[96:99], v[218:221], v[112:115]
	v_mfma_f32_16x16x32_bf16 v[112:115], v[92:95], v[214:217], v[112:115]
	s_barrier
	s_add_i32 s15, s15, s85
	s_mov_b32 m0, s15
	ds_read_b128 v[164:167], v200 offset:49152
	ds_read_b128 v[168:171], v200 offset:50176
	ds_read_b128 v[172:175], v200 offset:51200
	ds_read_b128 v[176:179], v200 offset:52224
	ds_read_b128 v[202:205], v200 offset:53248
	ds_read_b128 v[210:213], v200 offset:54272
	ds_read_b128 v[214:217], v200 offset:55296
	ds_read_b128 v[218:221], v200 offset:56320
	s_add_u32 s98, s76, 0x80
	s_addc_u32 s99, s77, 0
	global_load_lds_dwordx4 v2, s[98:99]
	s_add_i32 m0, s15, 0x2000
	s_add_u32 s76, s76, 0x80080
	s_addc_u32 s77, s77, 0
	s_add_i32 s15, s16, s85
	global_load_lds_dwordx4 v184, s[98:99]
	s_mov_b32 m0, s15
	s_nop 0
	global_load_lds_dwordx4 v2, s[76:77]
	s_add_i32 m0, s15, 0x2000
	s_nop 0
	global_load_lds_dwordx4 v184, s[76:77]
	s_mov_b32 m0, s92
	s_nop 0
	s_add_u32 s98, s78, 0xfff80080
	s_addc_u32 s99, s79, -1
	global_load_lds_dwordx4 v180, s[98:99]
	s_mov_b32 m0, s93
	s_nop 0
	global_load_lds_dwordx4 v182, s[98:99]
	s_waitcnt vmcnt(8)
	s_waitcnt lgkmcnt(0)
	s_barrier
	s_waitcnt lgkmcnt(0)
	v_mfma_f32_16x16x32_bf16 v[64:67], v[72:75], v[164:167], v[64:67]
	v_mfma_f32_16x16x32_bf16 v[64:67], v[76:79], v[168:171], v[64:67]
	v_mfma_f32_16x16x32_bf16 v[60:63], v[88:91], v[168:171], v[60:63]
	v_mfma_f32_16x16x32_bf16 v[60:63], v[84:87], v[164:167], v[60:63]
	v_mfma_f32_16x16x32_bf16 v[44:47], v[84:87], v[172:175], v[44:47]
	v_mfma_f32_16x16x32_bf16 v[44:47], v[88:91], v[176:179], v[44:47]
	v_mfma_f32_16x16x32_bf16 v[48:51], v[76:79], v[176:179], v[48:51]
	v_mfma_f32_16x16x32_bf16 v[48:51], v[72:75], v[172:175], v[48:51]
	v_mfma_f32_16x16x32_bf16 v[32:35], v[72:75], v[202:205], v[32:35]
	v_mfma_f32_16x16x32_bf16 v[32:35], v[76:79], v[210:213], v[32:35]
	v_mfma_f32_16x16x32_bf16 v[28:31], v[88:91], v[210:213], v[28:31]
	v_mfma_f32_16x16x32_bf16 v[28:31], v[84:87], v[202:205], v[28:31]
	v_mfma_f32_16x16x32_bf16 v[4:7], v[84:87], v[214:217], v[4:7]
	v_mfma_f32_16x16x32_bf16 v[4:7], v[88:91], v[218:221], v[4:7]
	v_mfma_f32_16x16x32_bf16 v[8:11], v[76:79], v[218:221], v[8:11]
	v_mfma_f32_16x16x32_bf16 v[8:11], v[72:75], v[214:217], v[8:11]
	s_add_i32 s21, s21, 2
	s_add_u32 s74, s74, 0x100
	s_addc_u32 s75, s75, 0
	s_add_u32 s19, s19, 0x100
	s_addc_u32 s20, s20, 0
	s_add_u32 s15, s74, 0xfff80080
	s_addc_u32 s16, s75, -1
	s_add_i32 s17, 0, 0x10000
	s_cmp_eq_u32 s21, 28
	s_cselect_b32 s79, s8, s16
	s_cselect_b32 s78, s11, s15
	s_cselect_b32 s77, s13, s20
	s_cselect_b32 s76, s18, s19
	s_add_i32 s15, 0, 0x14000
	s_cmp_gt_u32 s21, 29
	v_mfma_f32_16x16x32_bf16 v[56:59], v[92:95], v[164:167], v[56:59]
	v_mfma_f32_16x16x32_bf16 v[56:59], v[96:99], v[168:171], v[56:59]
	v_mfma_f32_16x16x32_bf16 v[52:55], v[104:107], v[168:171], v[52:55]
	v_mfma_f32_16x16x32_bf16 v[52:55], v[100:103], v[164:167], v[52:55]
	v_mfma_f32_16x16x32_bf16 v[36:39], v[100:103], v[172:175], v[36:39]
	v_mfma_f32_16x16x32_bf16 v[36:39], v[104:107], v[176:179], v[36:39]
	v_mfma_f32_16x16x32_bf16 v[40:43], v[96:99], v[176:179], v[40:43]
	v_mfma_f32_16x16x32_bf16 v[40:43], v[92:95], v[172:175], v[40:43]
	v_mfma_f32_16x16x32_bf16 v[24:27], v[92:95], v[202:205], v[24:27]
	v_mfma_f32_16x16x32_bf16 v[24:27], v[96:99], v[210:213], v[24:27]
	v_mfma_f32_16x16x32_bf16 v[20:23], v[104:107], v[210:213], v[20:23]
	v_mfma_f32_16x16x32_bf16 v[20:23], v[100:103], v[202:205], v[20:23]
	v_mfma_f32_16x16x32_bf16 v[12:15], v[100:103], v[214:217], v[12:15]
	v_mfma_f32_16x16x32_bf16 v[12:15], v[104:107], v[218:221], v[12:15]
	v_mfma_f32_16x16x32_bf16 v[16:19], v[96:99], v[218:221], v[16:19]
	v_mfma_f32_16x16x32_bf16 v[16:19], v[92:95], v[214:217], v[16:19]
	s_barrier
	s_cbranch_scc0 .LBB0_1238
	s_and_b64 vcc, exec, s[56:57]
	s_cbranch_vccnz .LBB0_1264
	s_and_saveexec_b64 s[18:19], s[38:39]
	s_cbranch_execnz .LBB0_1265
